# re-measure: fused GU + write-through stores in the QKV/BIN/BGRP epilogue
# speedup vs baseline: 1.0078x; 1.0078x over previous
; __device__ __forceinline__ unsigned cvt_pk_bf16(float lo, float hi) { unsigned r; asm volatile("v_cvt_pk_bf16_f32 %0, %1, %2" : "=v"(r) : "v"(lo), "v"(hi)); return r; }
; __device__ __forceinline__ float gelu_tanh(float x) { const float u = 0.7978845608028654f * (x + 0.044715f * x * x * x); return x * fast_rcp(1.0f + fast_exp2(-2.0f * LOG2E * u)); }
; __device__ __forceinline__ void load_rstd(float (&rsv)[2][4], const ssq_t* ssq, int row0) {
;     ssq_t t[2][4];
; #pragma unroll
;     for (int ai = 0; ai < 2; ++ai)
; #pragma unroll
;         for (int m = 0; m < 4; ++m) t[ai][m] = ssq[row0 + ai * HALF + m * 16];
; #pragma unroll
;     for (int ai = 0; ai < 2; ++ai)
; #pragma unroll
;         for (int m = 0; m < 4; ++m) rsv[ai][m] = __builtin_amdgcn_rsqf((float)t[ai][m] * (SSQ_INV / 1024.0f) + 1e-6f);
; }
; __device__ __forceinline__ void ssq_add(ssq_t* p, float v) { __hip_atomic_fetch_add((__attribute__((address_space(1))) ssq_t*)p, (ssq_t)(v * SSQ_SCALE), __ATOMIC_RELAXED, __HIP_MEMORY_SCOPE_AGENT); }
;     __device__ __forceinline__ void operator()(const f32x4 (&acc)[2][2][4][2], const Unit& u, int wr, int wc, int fr, int fq) const {
;         const int row0 = u.pm * BM + wr * 64 + fr, col0 = u.pn * BM + wc * 32 + 8 * fq;
;         float rsv[2][4]; load_rstd(rsv, ssq, row0);
; #pragma unroll
;         for (int ai = 0; ai < 2; ++ai)
; #pragma unroll
;             for (int m = 0; m < 4; ++m) { const int row = row0 + ai * HALF + m * 16; bf16_t* rowp = O + (size_t)row * ldc + col0; const float rs = rsv[ai][m];
; #pragma unroll
;                 for (int bj = 0; bj < 2; ++bj) { f32x4 v0 = acc[ai][bj][m][0] * rs, v1 = acc[ai][bj][m][1] * rs;
;                     if (ACT == 1) {
; #pragma unroll
;                         for (int j = 0; j < 4; ++j) { v0[j] = gelu_tanh(v0[j]); v1[j] = gelu_tanh(v1[j]); } }
;                     u32x4 w; w.x = cvt_pk_bf16(v0[0], v0[1]); w.y = cvt_pk_bf16(v0[2], v0[3]); w.z = cvt_pk_bf16(v1[0], v1[1]); w.w = cvt_pk_bf16(v1[2], v1[3]);
;                     *(u32x4*)(rowp + bj * HALF) = w; } }
.LBB0_357:
	v_mov_b32_e32 v143, v170
	s_lshl_b32 s11, s61, 8
	v_readfirstlane_b32 s10, v143
	s_ashr_i32 s61, s10, 2
	s_andn2_b32 s61, s61, 63
	s_lshr_b32 s10, s10, 1
	s_add_i32 s61, s61, s11
	s_lshl_b32 s11, s60, 8
	s_and_b32 s10, s10, 0x60
	v_and_or_b32 v142, v143, 15, s61
	s_or_b32 s10, s10, s11
	v_lshrrev_b32_e32 v143, 1, v143
	v_and_or_b32 v154, v143, 24, s10
	v_ashrrev_i32_e32 v143, 31, v142
	v_lshl_add_u64 v[152:153], v[142:143], 3, s[26:27]
	global_load_dwordx2 v[156:157], v[152:153], off
	global_load_dwordx2 v[162:163], v[152:153], off offset:128
	global_load_dwordx2 v[164:165], v[152:153], off offset:256
	global_load_dwordx2 v[166:167], v[152:153], off offset:384
	global_load_dwordx2 v[176:177], v[152:153], off offset:1024
	global_load_dwordx2 v[146:147], v[152:153], off offset:1152
	global_load_dwordx2 v[144:145], v[152:153], off offset:1280
	global_load_dwordx2 v[160:161], v[152:153], off offset:1408
	v_mul_lo_u32 v143, s28, v143
	v_ashrrev_i32_e32 v155, 31, v154
	v_lshlrev_b64 v[154:155], 1, v[154:155]
	s_and_b64 vcc, exec, s[8:9]
	s_waitcnt vmcnt(0)
	v_ffbh_u32_e32 v148, v157
	v_min_u32_e32 v148, 32, v148
	v_lshlrev_b64 v[152:153], v148, v[156:157]
	v_min_u32_e32 v150, 1, v152
	v_or_b32_e32 v150, v153, v150
	v_cvt_f32_u32_e32 v150, v150
	v_sub_u32_e32 v148, 32, v148
	v_ldexp_f32 v148, v150, v148
	v_fmamk_f32 v148, v148, 0x30800000, v223
	v_rsq_f32_e32 v158, v148
	v_ffbh_u32_e32 v148, v163
	v_min_u32_e32 v148, 32, v148
	v_lshlrev_b64 v[152:153], v148, v[162:163]
	v_min_u32_e32 v150, 1, v152
	v_or_b32_e32 v150, v153, v150
	v_cvt_f32_u32_e32 v150, v150
	v_sub_u32_e32 v148, 32, v148
	v_pk_mul_f32 v[126:127], v[126:127], v[158:159] op_sel_hi:[1,0]
	v_pk_mul_f32 v[124:125], v[124:125], v[158:159] op_sel_hi:[1,0]
	v_ldexp_f32 v148, v150, v148
	v_fmamk_f32 v148, v148, 0x30800000, v223
	v_rsq_f32_e32 v156, v148
	v_ffbh_u32_e32 v148, v165
	v_min_u32_e32 v148, 32, v148
	v_lshlrev_b64 v[152:153], v148, v[164:165]
	v_min_u32_e32 v150, 1, v152
	v_or_b32_e32 v150, v153, v150
	v_cvt_f32_u32_e32 v150, v150
	v_sub_u32_e32 v148, 32, v148
	v_pk_mul_f32 v[164:165], v[122:123], v[158:159] op_sel_hi:[1,0]
	v_pk_mul_f32 v[122:123], v[120:121], v[158:159] op_sel_hi:[1,0]
	v_ldexp_f32 v148, v150, v148
	v_fmamk_f32 v148, v148, 0x30800000, v223
	v_rsq_f32_e32 v152, v148
	v_ffbh_u32_e32 v148, v167
	v_min_u32_e32 v148, 32, v148
	v_lshlrev_b64 v[162:163], v148, v[166:167]
	v_min_u32_e32 v150, 1, v162
	v_or_b32_e32 v150, v163, v150
	v_cvt_f32_u32_e32 v150, v150
	v_sub_u32_e32 v148, 32, v148
	v_cvt_pk_bf16_f32 v120, v124, v125
	v_cvt_pk_bf16_f32 v121, v126, v127
	v_ldexp_f32 v148, v150, v148
	v_fmamk_f32 v148, v148, 0x30800000, v223
	v_rsq_f32_e32 v150, v148
	v_ffbh_u32_e32 v148, v177
	v_min_u32_e32 v148, 32, v148
	v_lshlrev_b64 v[162:163], v148, v[176:177]
	v_min_u32_e32 v153, 1, v162
	v_or_b32_e32 v153, v163, v153
	v_cvt_f32_u32_e32 v153, v153
	v_sub_u32_e32 v148, 32, v148
	v_mad_u64_u32 v[162:163], s[10:11], s28, v142, 0
	v_ldexp_f32 v148, v153, v148
	v_ffbh_u32_e32 v153, v147
	v_min_u32_e32 v153, 32, v153
	v_lshlrev_b64 v[146:147], v153, v[146:147]
	v_min_u32_e32 v146, 1, v146
	v_or_b32_e32 v146, v147, v146
	v_cvt_f32_u32_e32 v146, v146
	v_sub_u32_e32 v147, 32, v153
	v_cvt_pk_bf16_f32 v122, v122, v123
	v_cvt_pk_bf16_f32 v123, v164, v165
	v_ldexp_f32 v146, v146, v147
	v_ffbh_u32_e32 v147, v145
	v_min_u32_e32 v147, 32, v147
	v_lshlrev_b64 v[144:145], v147, v[144:145]
	v_min_u32_e32 v144, 1, v144
	v_or_b32_e32 v144, v145, v144
	v_cvt_f32_u32_e32 v144, v144
	v_sub_u32_e32 v145, 32, v147
	v_pk_mul_f32 v[116:117], v[116:117], v[158:159] op_sel_hi:[1,0]
	v_pk_mul_f32 v[118:119], v[118:119], v[158:159] op_sel_hi:[1,0]
	v_ldexp_f32 v144, v144, v145
	v_ffbh_u32_e32 v145, v161
	v_min_u32_e32 v145, 32, v145
	v_lshlrev_b64 v[160:161], v145, v[160:161]
	v_min_u32_e32 v147, 1, v160
	v_or_b32_e32 v147, v161, v147
	v_cvt_f32_u32_e32 v147, v147
	v_sub_u32_e32 v145, 32, v145
	v_pk_mul_f32 v[110:111], v[110:111], v[156:157] op_sel_hi:[1,0]
	v_pk_mul_f32 v[108:109], v[108:109], v[156:157] op_sel_hi:[1,0]
	v_ldexp_f32 v145, v147, v145
	v_fmamk_f32 v145, v145, 0x30800000, v223
	v_rsq_f32_e32 v160, v145
	v_mul_lo_u32 v145, s29, v142
	v_add3_u32 v163, v163, v143, v145
	v_lshl_add_u64 v[162:163], v[162:163], 1, s[30:31]
	v_lshl_add_u64 v[162:163], v[162:163], 0, v[154:155]
	global_store_dwordx4 v[162:163], v[120:123], off sc1
	v_pk_mul_f32 v[100:101], v[100:101], v[156:157] op_sel_hi:[1,0]
	v_pk_mul_f32 v[102:103], v[102:103], v[156:157] op_sel_hi:[1,0]
	v_pk_mul_f32 v[120:121], v[114:115], v[158:159] op_sel_hi:[1,0]
	v_pk_mul_f32 v[114:115], v[112:113], v[158:159] op_sel_hi:[1,0]
	v_cvt_pk_bf16_f32 v112, v116, v117
	v_cvt_pk_bf16_f32 v113, v118, v119
	v_pk_mul_f32 v[94:95], v[94:95], v[152:153] op_sel_hi:[1,0]
	v_cvt_pk_bf16_f32 v114, v114, v115
	v_cvt_pk_bf16_f32 v115, v120, v121
	global_store_dwordx4 v[162:163], v[112:115], off offset:256 sc1
	v_pk_mul_f32 v[92:93], v[92:93], v[152:153] op_sel_hi:[1,0]
	v_pk_mul_f32 v[84:85], v[84:85], v[152:153] op_sel_hi:[1,0]
	v_or_b32_e32 v112, 16, v142
	v_mul_lo_u32 v114, s29, v112
	v_mad_u64_u32 v[112:113], s[10:11], s28, v112, 0
	v_add3_u32 v113, v113, v143, v114
	v_lshl_add_u64 v[112:113], v[112:113], 1, s[30:31]
	v_lshl_add_u64 v[112:113], v[112:113], 0, v[154:155]
	v_pk_mul_f32 v[114:115], v[106:107], v[156:157] op_sel_hi:[1,0]
	v_pk_mul_f32 v[106:107], v[104:105], v[156:157] op_sel_hi:[1,0]
	v_cvt_pk_bf16_f32 v104, v108, v109
	v_cvt_pk_bf16_f32 v105, v110, v111
	v_pk_mul_f32 v[86:87], v[86:87], v[152:153] op_sel_hi:[1,0]
	v_cvt_pk_bf16_f32 v106, v106, v107
	v_cvt_pk_bf16_f32 v107, v114, v115
	global_store_dwordx4 v[112:113], v[104:107], off sc1
; __device__ __forceinline__ unsigned cvt_pk_bf16(float lo, float hi) { unsigned r; asm volatile("v_cvt_pk_bf16_f32 %0, %1, %2" : "=v"(r) : "v"(lo), "v"(hi)); return r; }
; __device__ __forceinline__ float gelu_tanh(float x) { const float u = 0.7978845608028654f * (x + 0.044715f * x * x * x); return x * fast_rcp(1.0f + fast_exp2(-2.0f * LOG2E * u)); }
;     __device__ __forceinline__ void operator()(const f32x4 (&acc)[2][2][4][2], const Unit& u, int wr, int wc, int fr, int fq) const {
;     ...
;             for (int m = 0; m < 4; ++m) { const int row = row0 + ai * HALF + m * 16; bf16_t* rowp = O + (size_t)row * ldc + col0; const float rs = rsv[ai][m];
; #pragma unroll
;                 for (int bj = 0; bj < 2; ++bj) { f32x4 v0 = acc[ai][bj][m][0] * rs, v1 = acc[ai][bj][m][1] * rs;
;                     if (ACT == 1) {
; #pragma unroll
;                         for (int j = 0; j < 4; ++j) { v0[j] = gelu_tanh(v0[j]); v1[j] = gelu_tanh(v1[j]); } }
;                     u32x4 w; w.x = cvt_pk_bf16(v0[0], v0[1]); w.y = cvt_pk_bf16(v0[2], v0[3]); w.z = cvt_pk_bf16(v1[0], v1[1]); w.w = cvt_pk_bf16(v1[2], v1[3]);
;                     *(u32x4*)(rowp + bj * HALF) = w; } }
	v_pk_mul_f32 v[78:79], v[78:79], v[150:151] op_sel_hi:[1,0]
	v_pk_mul_f32 v[76:77], v[76:77], v[150:151] op_sel_hi:[1,0]
	v_pk_mul_f32 v[104:105], v[98:99], v[156:157] op_sel_hi:[1,0]
	v_pk_mul_f32 v[98:99], v[96:97], v[156:157] op_sel_hi:[1,0]
	v_cvt_pk_bf16_f32 v96, v100, v101
	v_cvt_pk_bf16_f32 v97, v102, v103
	v_pk_mul_f32 v[68:69], v[68:69], v[150:151] op_sel_hi:[1,0]
	v_cvt_pk_bf16_f32 v98, v98, v99
	v_cvt_pk_bf16_f32 v99, v104, v105
	global_store_dwordx4 v[112:113], v[96:99], off offset:256 sc1
	v_fmamk_f32 v148, v148, 0x30800000, v223
	v_pk_mul_f32 v[70:71], v[70:71], v[150:151] op_sel_hi:[1,0]
	v_or_b32_e32 v96, 32, v142
	v_mul_lo_u32 v98, s29, v96
	v_mad_u64_u32 v[96:97], s[10:11], s28, v96, 0
	v_add3_u32 v97, v97, v143, v98
	v_lshl_add_u64 v[96:97], v[96:97], 1, s[30:31]
	v_lshl_add_u64 v[96:97], v[96:97], 0, v[154:155]
	v_pk_mul_f32 v[98:99], v[90:91], v[152:153] op_sel_hi:[1,0]
	v_pk_mul_f32 v[90:91], v[88:89], v[152:153] op_sel_hi:[1,0]
	v_cvt_pk_bf16_f32 v88, v92, v93
	v_cvt_pk_bf16_f32 v89, v94, v95
	v_rsq_f32_e32 v148, v148
	v_cvt_pk_bf16_f32 v90, v90, v91
	v_cvt_pk_bf16_f32 v91, v98, v99
	global_store_dwordx4 v[96:97], v[88:91], off sc1
	v_pk_mul_f32 v[62:63], v[62:63], v[148:149] op_sel_hi:[1,0]
	v_pk_mul_f32 v[60:61], v[60:61], v[148:149] op_sel_hi:[1,0]
	v_pk_mul_f32 v[88:89], v[82:83], v[152:153] op_sel_hi:[1,0]
	v_pk_mul_f32 v[82:83], v[80:81], v[152:153] op_sel_hi:[1,0]
	v_cvt_pk_bf16_f32 v80, v84, v85
	v_cvt_pk_bf16_f32 v81, v86, v87
	v_pk_mul_f32 v[52:53], v[52:53], v[148:149] op_sel_hi:[1,0]
	v_cvt_pk_bf16_f32 v82, v82, v83
	v_cvt_pk_bf16_f32 v83, v88, v89
	global_store_dwordx4 v[96:97], v[80:83], off offset:256 sc1
	v_fmamk_f32 v146, v146, 0x30800000, v223
	v_pk_mul_f32 v[54:55], v[54:55], v[148:149] op_sel_hi:[1,0]
	v_or_b32_e32 v80, 48, v142
	v_mul_lo_u32 v82, s29, v80
	v_mad_u64_u32 v[80:81], s[10:11], s28, v80, 0
	v_add3_u32 v81, v81, v143, v82
	v_lshl_add_u64 v[80:81], v[80:81], 1, s[30:31]
	v_lshl_add_u64 v[80:81], v[80:81], 0, v[154:155]
	v_pk_mul_f32 v[82:83], v[74:75], v[150:151] op_sel_hi:[1,0]
	v_pk_mul_f32 v[74:75], v[72:73], v[150:151] op_sel_hi:[1,0]
	v_cvt_pk_bf16_f32 v72, v76, v77
	v_cvt_pk_bf16_f32 v73, v78, v79
	v_rsq_f32_e32 v146, v146
	v_cvt_pk_bf16_f32 v74, v74, v75
	v_cvt_pk_bf16_f32 v75, v82, v83
	global_store_dwordx4 v[80:81], v[72:75], off sc1
	v_pk_mul_f32 v[46:47], v[46:47], v[146:147] op_sel_hi:[1,0]
	v_pk_mul_f32 v[44:45], v[44:45], v[146:147] op_sel_hi:[1,0]
	v_pk_mul_f32 v[72:73], v[66:67], v[150:151] op_sel_hi:[1,0]
	v_pk_mul_f32 v[66:67], v[64:65], v[150:151] op_sel_hi:[1,0]
	v_cvt_pk_bf16_f32 v64, v68, v69
	v_cvt_pk_bf16_f32 v65, v70, v71
	v_pk_mul_f32 v[36:37], v[36:37], v[146:147] op_sel_hi:[1,0]
	v_cvt_pk_bf16_f32 v66, v66, v67
	v_cvt_pk_bf16_f32 v67, v72, v73
	global_store_dwordx4 v[80:81], v[64:67], off offset:256 sc1
	v_fmamk_f32 v144, v144, 0x30800000, v223
	v_pk_mul_f32 v[38:39], v[38:39], v[146:147] op_sel_hi:[1,0]
	v_add_u32_e32 v64, 0x80, v142
	v_ashrrev_i32_e32 v65, 31, v64
	v_mul_lo_u32 v66, s28, v65
	v_mul_lo_u32 v67, s29, v64
	v_mad_u64_u32 v[64:65], s[10:11], s28, v64, 0
	v_add3_u32 v65, v65, v66, v67
	v_lshl_add_u64 v[64:65], v[64:65], 1, s[30:31]
	v_lshl_add_u64 v[64:65], v[64:65], 0, v[154:155]
	v_pk_mul_f32 v[66:67], v[58:59], v[148:149] op_sel_hi:[1,0]
	v_pk_mul_f32 v[58:59], v[56:57], v[148:149] op_sel_hi:[1,0]
	v_cvt_pk_bf16_f32 v56, v60, v61
	v_cvt_pk_bf16_f32 v57, v62, v63
	v_rsq_f32_e32 v144, v144
	v_cvt_pk_bf16_f32 v58, v58, v59
	v_cvt_pk_bf16_f32 v59, v66, v67
	global_store_dwordx4 v[64:65], v[56:59], off sc1
	v_pk_mul_f32 v[30:31], v[30:31], v[144:145] op_sel_hi:[1,0]
; __device__ __forceinline__ unsigned cvt_pk_bf16(float lo, float hi) { unsigned r; asm volatile("v_cvt_pk_bf16_f32 %0, %1, %2" : "=v"(r) : "v"(lo), "v"(hi)); return r; }
; __device__ __forceinline__ float gelu_tanh(float x) { const float u = 0.7978845608028654f * (x + 0.044715f * x * x * x); return x * fast_rcp(1.0f + fast_exp2(-2.0f * LOG2E * u)); }
;     __device__ __forceinline__ void operator()(const f32x4 (&acc)[2][2][4][2], const Unit& u, int wr, int wc, int fr, int fq) const {
;     ...
;             for (int m = 0; m < 4; ++m) { const int row = row0 + ai * HALF + m * 16; bf16_t* rowp = O + (size_t)row * ldc + col0; const float rs = rsv[ai][m];
; #pragma unroll
;                 for (int bj = 0; bj < 2; ++bj) { f32x4 v0 = acc[ai][bj][m][0] * rs, v1 = acc[ai][bj][m][1] * rs;
;                     if (ACT == 1) {
; #pragma unroll
;                         for (int j = 0; j < 4; ++j) { v0[j] = gelu_tanh(v0[j]); v1[j] = gelu_tanh(v1[j]); } }
;                     u32x4 w; w.x = cvt_pk_bf16(v0[0], v0[1]); w.y = cvt_pk_bf16(v0[2], v0[3]); w.z = cvt_pk_bf16(v1[0], v1[1]); w.w = cvt_pk_bf16(v1[2], v1[3]);
;                     *(u32x4*)(rowp + bj * HALF) = w; } }
	v_pk_mul_f32 v[28:29], v[28:29], v[144:145] op_sel_hi:[1,0]
	v_pk_mul_f32 v[56:57], v[50:51], v[148:149] op_sel_hi:[1,0]
	v_pk_mul_f32 v[50:51], v[48:49], v[148:149] op_sel_hi:[1,0]
	v_cvt_pk_bf16_f32 v48, v52, v53
	v_cvt_pk_bf16_f32 v49, v54, v55
	v_pk_mul_f32 v[20:21], v[20:21], v[144:145] op_sel_hi:[1,0]
	v_cvt_pk_bf16_f32 v50, v50, v51
	v_cvt_pk_bf16_f32 v51, v56, v57
	global_store_dwordx4 v[64:65], v[48:51], off offset:256 sc1
	v_pk_mul_f32 v[22:23], v[22:23], v[144:145] op_sel_hi:[1,0]
	v_pk_mul_f32 v[14:15], v[14:15], v[160:161] op_sel_hi:[1,0]
	v_add_u32_e32 v48, 0x90, v142
	v_ashrrev_i32_e32 v49, 31, v48
	v_mul_lo_u32 v50, s28, v49
	v_mul_lo_u32 v51, s29, v48
	v_mad_u64_u32 v[48:49], s[10:11], s28, v48, 0
	v_add3_u32 v49, v49, v50, v51
	v_lshl_add_u64 v[48:49], v[48:49], 1, s[30:31]
	v_lshl_add_u64 v[48:49], v[48:49], 0, v[154:155]
	v_pk_mul_f32 v[50:51], v[42:43], v[146:147] op_sel_hi:[1,0]
	v_pk_mul_f32 v[42:43], v[40:41], v[146:147] op_sel_hi:[1,0]
	v_cvt_pk_bf16_f32 v40, v44, v45
	v_cvt_pk_bf16_f32 v41, v46, v47
	v_pk_mul_f32 v[12:13], v[12:13], v[160:161] op_sel_hi:[1,0]
	v_cvt_pk_bf16_f32 v42, v42, v43
	v_cvt_pk_bf16_f32 v43, v50, v51
	global_store_dwordx4 v[48:49], v[40:43], off sc1
	v_pk_mul_f32 v[6:7], v[6:7], v[160:161] op_sel_hi:[1,0]
	v_pk_mul_f32 v[4:5], v[4:5], v[160:161] op_sel_hi:[1,0]
	v_pk_mul_f32 v[40:41], v[34:35], v[146:147] op_sel_hi:[1,0]
	v_pk_mul_f32 v[34:35], v[32:33], v[146:147] op_sel_hi:[1,0]
	v_cvt_pk_bf16_f32 v32, v36, v37
	v_cvt_pk_bf16_f32 v33, v38, v39
	s_nop 0
	v_cvt_pk_bf16_f32 v34, v34, v35
	v_cvt_pk_bf16_f32 v35, v40, v41
	global_store_dwordx4 v[48:49], v[32:35], off offset:256 sc1
	s_nop 1
	v_add_u32_e32 v32, 0xa0, v142
	v_ashrrev_i32_e32 v33, 31, v32
	v_mul_lo_u32 v34, s28, v33
	v_mul_lo_u32 v35, s29, v32
	v_mad_u64_u32 v[32:33], s[10:11], s28, v32, 0
	v_add3_u32 v33, v33, v34, v35
	v_lshl_add_u64 v[32:33], v[32:33], 1, s[30:31]
	v_lshl_add_u64 v[32:33], v[32:33], 0, v[154:155]
	v_pk_mul_f32 v[34:35], v[26:27], v[144:145] op_sel_hi:[1,0]
	v_pk_mul_f32 v[26:27], v[24:25], v[144:145] op_sel_hi:[1,0]
	v_cvt_pk_bf16_f32 v24, v28, v29
	v_cvt_pk_bf16_f32 v25, v30, v31
	s_nop 0
	v_cvt_pk_bf16_f32 v26, v26, v27
	v_cvt_pk_bf16_f32 v27, v34, v35
	global_store_dwordx4 v[32:33], v[24:27], off sc1
	s_nop 1
	v_pk_mul_f32 v[24:25], v[18:19], v[144:145] op_sel_hi:[1,0]
	v_pk_mul_f32 v[18:19], v[16:17], v[144:145] op_sel_hi:[1,0]
	v_cvt_pk_bf16_f32 v16, v20, v21
	v_cvt_pk_bf16_f32 v17, v22, v23
	s_nop 0
	v_cvt_pk_bf16_f32 v18, v18, v19
	v_cvt_pk_bf16_f32 v19, v24, v25
	global_store_dwordx4 v[32:33], v[16:19], off offset:256 sc1
	s_nop 1
	v_add_u32_e32 v16, 0xb0, v142
	v_ashrrev_i32_e32 v17, 31, v16
	v_mul_lo_u32 v18, s28, v17
	v_mul_lo_u32 v19, s29, v16
	v_mad_u64_u32 v[16:17], s[10:11], s28, v16, 0
	v_add3_u32 v17, v17, v18, v19
	v_lshl_add_u64 v[16:17], v[16:17], 1, s[30:31]
	v_lshl_add_u64 v[16:17], v[16:17], 0, v[154:155]
	v_pk_mul_f32 v[18:19], v[10:11], v[160:161] op_sel_hi:[1,0]
	v_pk_mul_f32 v[10:11], v[8:9], v[160:161] op_sel_hi:[1,0]
	v_cvt_pk_bf16_f32 v8, v12, v13
	v_cvt_pk_bf16_f32 v9, v14, v15
	s_mov_b64 s[10:11], -1
	v_cvt_pk_bf16_f32 v10, v10, v11
	v_cvt_pk_bf16_f32 v11, v18, v19
	global_store_dwordx4 v[16:17], v[8:11], off sc1
	s_nop 1
	v_pk_mul_f32 v[8:9], v[2:3], v[160:161] op_sel_hi:[1,0]
	v_pk_mul_f32 v[2:3], v[0:1], v[160:161] op_sel_hi:[1,0]
	v_cvt_pk_bf16_f32 v0, v4, v5
	v_cvt_pk_bf16_f32 v1, v6, v7
	s_nop 0
	v_cvt_pk_bf16_f32 v2, v2, v3
	v_cvt_pk_bf16_f32 v3, v8, v9
	global_store_dwordx4 v[16:17], v[0:3], off offset:256 sc1
	s_cbranch_vccnz .LBB0_345
	s_andn2_b64 vcc, exec, s[40:41]
	s_cbranch_vccnz .LBB0_344
	s_barrier
	s_branch .LBB0_344
